# v14 plus attention loop exit test shortened: v_cmp result feeds s_cbranch_vccz directly (scalar ballot chain removed, operand wait states re-padded)
# speedup vs baseline: 1.0019x; 1.0019x over previous
; __device__ __forceinline__ void attn_phase(const bf16* Q, const bf16* K, const bf16* V, bf16* O, int gw, int ngw, int lane) {
;     ...
;         ATT_LOAD(t0 + 14)
;         for (int s_hi = t0 + 14; s_hi >= 0; s_hi -= 16) {
;             const bf16x8 ka0 = kn0, ka1 = kn1;
;             unsigned short vv[4][4];
; #pragma unroll
;             for (int j = 0; j < 4; ++j)
; #pragma unroll
;                 for (int dt = 0; dt < 4; ++dt) vv[dt][j] = vn[dt][j];
;             ATT_LOAD(s_hi - 16)
;             f32x4 z = (f32x4){0.f, 0.f, 0.f, 0.f};
;             z = __builtin_amdgcn_mfma_f32_16x16x32_bf16(ka0, qb0, z, 0, 0, 0);
;             z = __builtin_amdgcn_mfma_f32_16x16x32_bf16(ka1, qb1, z, 0, 0, 0);
;             float dd[4], sg[4];
; #pragma unroll
;             for (int i = 0; i < 4; ++i) {
;                 const int s = s_hi - (4 * fq + i);
;                 const bool valid = (s >= 0) && (s < tq);
;                 const float e = __builtin_amdgcn_exp2f(fminf(z[i], 100.f));
;                 const float d = __builtin_amdgcn_rcpf(1.0f + e);
;                 dd[i] = valid ? d : 1.f; sg[i] = valid ? e * d : 0.f;
;             }
;             const float c1 = dd[0], c2 = c1 * dd[1], c3 = c2 * dd[2], g = c3 * dd[3];
;             const float g0 = __shfl(g, fr), g1 = __shfl(g, fr + 16), g2 = __shfl(g, fr + 32), g3 = __shfl(g, fr + 48);
;             float pre = carry;
;             if (fq > 0) pre *= g0;
;             if (fq > 1) pre *= g1;
;             if (fq > 2) pre *= g2;
;             carry = carry * ((g0 * g1) * (g2 * g3));
;             const float p0 = sg[0] * pre, p1 = sg[1] * (pre * c1), p2 = sg[2] * (pre * c2), p3 = sg[3] * (pre * c3);
;             bf16x8 pb; { const unsigned w0 = pk2(p0, p1), w1 = pk2(p2, p3); pb[0] = (short)(w0 & 0xffff); pb[1] = (short)(w0 >> 16); pb[2] = (short)(w1 & 0xffff); pb[3] = (short)(w1 >> 16); pb[4] = 0; pb[5] = 0; pb[6] = 0; pb[7] = 0; }
; #pragma unroll
;             for (int dt = 0; dt < 4; ++dt) {
;                 bf16x8 va; va[0] = (short)vv[dt][0]; va[1] = (short)vv[dt][1]; va[2] = (short)vv[dt][2]; va[3] = (short)vv[dt][3]; va[4] = 0; va[5] = 0; va[6] = 0; va[7] = 0;
;                 o[dt] = __builtin_amdgcn_mfma_f32_16x16x32_bf16(va, pb, o[dt], 0, 0, 0);
;             }
;             if (__builtin_amdgcn_ballot_w64(carry != 0.f) == 0ull) break;
.LBB0_2225:
	v_mov_b32_e32 v73, v236
	v_lshl_add_u64 v[0:1], s[4:5], 0, v[72:73]
	v_lshlrev_b64 v[0:1], 11, v[0:1]
	v_lshlrev_b64 v[4:5], 11, v[68:69]
	v_lshl_add_u64 v[0:1], v[60:61], 0, v[0:1]
	v_lshlrev_b64 v[2:3], 11, v[70:71]
	v_lshl_add_u64 v[32:33], v[60:61], 0, v[4:5]
	v_lshlrev_b64 v[4:5], 11, v[66:67]
	v_lshl_add_u64 v[2:3], v[60:61], 0, v[2:3]
	v_lshl_add_u64 v[34:35], v[60:61], 0, v[4:5]
	global_load_ushort v55, v[0:1], off offset:96
	global_load_ushort v73, v[2:3], off offset:96
	global_load_ushort v82, v[32:33], off offset:96
	global_load_ushort v83, v[34:35], off offset:96
	global_load_ushort v8, v[0:1], off offset:64
	global_load_ushort v9, v[2:3], off offset:64
	global_load_ushort v10, v[32:33], off offset:64
	global_load_ushort v11, v[34:35], off offset:64
	global_load_ushort v4, v[0:1], off offset:32
	global_load_ushort v5, v[2:3], off offset:32
	global_load_ushort v6, v[32:33], off offset:32
	global_load_ushort v7, v[34:35], off offset:32
	s_nop 0
	global_load_ushort v0, v[0:1], off
	s_nop 0
	global_load_ushort v1, v[2:3], off
	global_load_ushort v92, v[32:33], off
	global_load_ushort v93, v[34:35], off
	s_add_i32 s12, s11, -16
	v_add_u32_e32 v2, s12, v78
	v_max_i32_e32 v2, 0, v2
	v_mov_b32_e32 v3, v236
	v_lshl_add_u64 v[2:3], s[4:5], 0, v[2:3]
	v_lshlrev_b64 v[2:3], 11, v[2:3]
	v_add_u32_e32 v32, s11, v77
	v_lshl_add_u64 v[64:65], v[62:63], 0, v[2:3]
	v_add_u32_e32 v2, -16, v32
	v_max_i32_e32 v2, 0, v2
	v_mov_b32_e32 v3, v236
	v_lshl_add_u64 v[66:67], s[4:5], 0, v[2:3]
	v_subrev_u32_e32 v2, 17, v32
	v_max_i32_e32 v2, 0, v2
	v_lshl_add_u64 v[68:69], s[4:5], 0, v[2:3]
	v_add_u32_e32 v2, s12, v76
	v_max_i32_e32 v2, 0, v2
	v_lshl_add_u64 v[70:71], s[4:5], 0, v[2:3]
	v_add_u32_e32 v2, s12, v75
	v_max_i32_e32 v72, 0, v2
	v_cmp_lt_u32_e32 vcc, v32, v58
	v_sub_u32_e32 v35, s11, v50
	v_cmp_lt_u32_e64 s[44:45], v35, v58
	s_pack_ll_b32_b16 s6, 0, 0
	v_mov_b32_e32 v237, v236
	s_mov_b64 s[8:9], 0
	s_waitcnt vmcnt(16)
	v_mfma_f32_16x16x32_bf16 v[84:87], v[106:109], v[36:39], 0
	v_mfma_f32_16x16x32_bf16 v[84:87], v[110:113], v[40:43], v[84:87]
	global_load_dwordx4 v[106:109], v[64:65], off
	global_load_dwordx4 v[110:113], v[64:65], off offset:64
	s_nop 7
	v_max_f32_e32 v2, v84, v84
	v_min_f32_e32 v2, 0x42c80000, v2
	v_exp_f32_e32 v2, v2
	v_sub_u32_e32 v84, s11, v49
	s_mov_b32 s11, s12
	v_add_f32_e32 v3, 1.0, v2
	v_rcp_f32_e32 v3, v3
	s_nop 0
	v_mul_f32_e32 v2, v2, v3
	v_cndmask_b32_e32 v89, 0, v2, vcc
	v_add_u32_e32 v2, -1, v32
	v_cndmask_b32_e32 v88, 1.0, v3, vcc
	v_cmp_lt_u32_e32 vcc, v2, v58
	v_max_f32_e32 v2, v85, v85
	v_min_f32_e32 v2, 0x42c80000, v2
	v_exp_f32_e32 v2, v2
	v_or_b32_e32 v85, v232, v59
	v_lshlrev_b32_e32 v85, 2, v85
	v_add_f32_e32 v3, 1.0, v2
	v_rcp_f32_e32 v3, v3
	s_nop 0
	v_mul_f32_e32 v2, v2, v3
	v_cndmask_b32_e32 v90, 0, v2, vcc
	v_max_f32_e32 v2, v86, v86
	v_min_f32_e32 v2, 0x42c80000, v2
	v_exp_f32_e32 v2, v2
	v_cndmask_b32_e32 v34, 1.0, v3, vcc
	v_cmp_lt_u32_e32 vcc, v84, v51
	v_add_f32_e32 v3, 1.0, v2
	v_rcp_f32_e32 v32, v3
	v_max_f32_e32 v3, v87, v87
	v_min_f32_e32 v3, 0x42c80000, v3
	v_exp_f32_e32 v3, v3
	v_cndmask_b32_e64 v35, 1.0, v32, s[44:45]
	v_add_f32_e32 v33, 1.0, v3
	v_rcp_f32_e32 v33, v33
	s_nop 0
	v_pk_mul_f32 v[2:3], v[2:3], v[32:33]
	v_mul_f32_e32 v32, v88, v34
	v_cndmask_b32_e32 v84, 1.0, v33, vcc
	v_mul_f32_e32 v33, v35, v32
	v_mul_f32_e32 v86, v84, v33
	ds_bpermute_b32 v34, v85, v86
	ds_bpermute_b32 v84, v79, v86
	ds_bpermute_b32 v35, v80, v86
	ds_bpermute_b32 v85, v81, v86
	v_cndmask_b32_e32 v3, 0, v3, vcc
	s_waitcnt lgkmcnt(3)
	v_mul_f32_e32 v86, v53, v34
	v_cndmask_b32_e64 v86, v86, v53, s[38:39]
	s_waitcnt lgkmcnt(2)
	v_mul_f32_e32 v87, v86, v84
	v_cndmask_b32_e64 v86, v86, v87, s[40:41]
	s_waitcnt lgkmcnt(1)
	v_mul_f32_e32 v87, v86, v35
	v_cndmask_b32_e64 v86, v86, v87, s[42:43]
	s_waitcnt lgkmcnt(0)
	v_pk_mul_f32 v[34:35], v[34:35], v[84:85]
	v_mul_f32_e32 v84, v88, v86
	v_mul_f32_e32 v34, v34, v35
	v_mul_f32_e32 v35, v89, v86
	v_mul_f32_e32 v84, v90, v84
	v_pk_mul_f32 v[32:33], v[32:33], v[86:87] op_sel_hi:[1,0]
	v_cvt_pk_bf16_f32 v234, v35, v84
	s_waitcnt vmcnt(2)
	v_perm_b32 v84, v92, v93, s0
	v_perm_b32 v85, v0, v1, s0
	v_mov_b32_e32 v86, s6
	v_mov_b32_e32 v87, s6
	v_cndmask_b32_e64 v2, 0, v2, s[44:45]
	v_pk_mul_f32 v[2:3], v[2:3], v[32:33]
	v_mul_f32_e32 v53, v53, v34
	v_cvt_pk_bf16_f32 v235, v2, v3
	v_cmp_neq_f32_e32 vcc, 0, v53
	s_nop 0
	v_mfma_f32_16x16x32_bf16 v[16:19], v[84:87], v[234:237], v[16:19]
	v_perm_b32 v84, v6, v7, s0
	v_perm_b32 v85, v4, v5, s0
	s_nop 1
	v_mfma_f32_16x16x32_bf16 v[20:23], v[84:87], v[234:237], v[20:23]
	v_perm_b32 v84, v10, v11, s0
	v_perm_b32 v85, v8, v9, s0
	s_nop 1
	v_mfma_f32_16x16x32_bf16 v[24:27], v[84:87], v[234:237], v[24:27]
	v_perm_b32 v84, v82, v83, s0
	v_perm_b32 v85, v55, v73, s0
	s_nop 1
	v_mfma_f32_16x16x32_bf16 v[28:31], v[84:87], v[234:237], v[28:31]
	s_cbranch_vccz .LBB0_2223
	s_cmp_lt_i32 s11, 0
	s_cbranch_scc0 .LBB0_2225
	s_branch .LBB0_2223
